# v9 + all 7 GEMM K-loop heads aligned to 64 B
# baseline (speedup 1.0000x reference)
.LBB0_246:
	s_ashr_i32 s13, s12, 31
	s_lshl_b64 s[14:15], s[12:13], 20
	s_add_u32 s14, s38, s14
	s_addc_u32 s15, s39, s15
	s_and_b64 s[16:17], s[6:7], exec
	s_cselect_b32 s9, s15, s31
	s_cselect_b32 s13, s14, s30
	s_ashr_i32 s27, s26, 31
	s_lshl_b64 s[16:17], s[26:27], 20
	s_add_u32 s16, s40, s16
	s_addc_u32 s17, s41, s17
	s_and_b64 s[36:37], s[6:7], exec
	s_cselect_b32 s27, s17, s35
	s_cselect_b32 s29, s16, s34
	s_add_u32 s30, s30, 0x80080
	s_addc_u32 s31, s31, 0
	s_add_u32 s68, s34, 0x100
	v_mov_b32_e32 v2, 0
	s_addc_u32 s69, s35, 0
	s_mov_b32 s70, -2
	s_waitcnt lgkmcnt(0)
	v_mov_b32_e32 v3, v2
	v_mov_b32_e32 v4, v2
	v_mov_b32_e32 v5, v2
	v_mov_b32_e32 v6, v2
	v_mov_b32_e32 v7, v2
	v_mov_b32_e32 v8, v2
	v_mov_b32_e32 v9, v2
	v_mov_b32_e32 v18, v2
	v_mov_b32_e32 v19, v2
	v_mov_b32_e32 v20, v2
	v_mov_b32_e32 v21, v2
	v_mov_b32_e32 v22, v2
	v_mov_b32_e32 v23, v2
	v_mov_b32_e32 v24, v2
	v_mov_b32_e32 v25, v2
	v_mov_b32_e32 v34, v2
	v_mov_b32_e32 v35, v2
	v_mov_b32_e32 v36, v2
	v_mov_b32_e32 v37, v2
	v_mov_b32_e32 v38, v2
	v_mov_b32_e32 v39, v2
	v_mov_b32_e32 v40, v2
	v_mov_b32_e32 v41, v2
	v_mov_b32_e32 v50, v2
	v_mov_b32_e32 v51, v2
	v_mov_b32_e32 v52, v2
	v_mov_b32_e32 v53, v2
	v_mov_b32_e32 v54, v2
	v_mov_b32_e32 v55, v2
	v_mov_b32_e32 v56, v2
	v_mov_b32_e32 v57, v2
	v_mov_b32_e32 v10, v2
	v_mov_b32_e32 v11, v2
	v_mov_b32_e32 v12, v2
	v_mov_b32_e32 v13, v2
	v_mov_b32_e32 v14, v2
	v_mov_b32_e32 v15, v2
	v_mov_b32_e32 v16, v2
	v_mov_b32_e32 v17, v2
	v_mov_b32_e32 v26, v2
	v_mov_b32_e32 v27, v2
	v_mov_b32_e32 v28, v2
	v_mov_b32_e32 v29, v2
	v_mov_b32_e32 v30, v2
	v_mov_b32_e32 v31, v2
	v_mov_b32_e32 v32, v2
	v_mov_b32_e32 v33, v2
	v_mov_b32_e32 v42, v2
	v_mov_b32_e32 v43, v2
	v_mov_b32_e32 v44, v2
	v_mov_b32_e32 v45, v2
	v_mov_b32_e32 v46, v2
	v_mov_b32_e32 v47, v2
	v_mov_b32_e32 v48, v2
	v_mov_b32_e32 v49, v2
	v_mov_b32_e32 v58, v2
	v_mov_b32_e32 v59, v2
	v_mov_b32_e32 v60, v2
	v_mov_b32_e32 v61, v2
	v_mov_b32_e32 v62, v2
	v_mov_b32_e32 v63, v2
	v_mov_b32_e32 v64, v2
	v_mov_b32_e32 v65, v2
	v_mov_b32_e32 v66, v2
	v_mov_b32_e32 v67, v2
	v_mov_b32_e32 v68, v2
	v_mov_b32_e32 v69, v2
	v_mov_b32_e32 v70, v2
	v_mov_b32_e32 v71, v2
	v_mov_b32_e32 v72, v2
	v_mov_b32_e32 v73, v2
	v_mov_b32_e32 v82, v2
	v_mov_b32_e32 v83, v2
	v_mov_b32_e32 v84, v2
	v_mov_b32_e32 v85, v2
	v_mov_b32_e32 v86, v2
	v_mov_b32_e32 v87, v2
	v_mov_b32_e32 v88, v2
	v_mov_b32_e32 v89, v2
	v_mov_b32_e32 v98, v2
	v_mov_b32_e32 v99, v2
	v_mov_b32_e32 v100, v2
	v_mov_b32_e32 v101, v2
	v_mov_b32_e32 v102, v2
	v_mov_b32_e32 v103, v2
	v_mov_b32_e32 v104, v2
	v_mov_b32_e32 v105, v2
	v_mov_b32_e32 v114, v2
	v_mov_b32_e32 v115, v2
	v_mov_b32_e32 v116, v2
	v_mov_b32_e32 v117, v2
	v_mov_b32_e32 v118, v2
	v_mov_b32_e32 v119, v2
	v_mov_b32_e32 v120, v2
	v_mov_b32_e32 v121, v2
	v_mov_b32_e32 v74, v2
	v_mov_b32_e32 v75, v2
	v_mov_b32_e32 v76, v2
	v_mov_b32_e32 v77, v2
	v_mov_b32_e32 v78, v2
	v_mov_b32_e32 v79, v2
	v_mov_b32_e32 v80, v2
	v_mov_b32_e32 v81, v2
	v_mov_b32_e32 v90, v2
	v_mov_b32_e32 v91, v2
	v_mov_b32_e32 v92, v2
	v_mov_b32_e32 v93, v2
	v_mov_b32_e32 v94, v2
	v_mov_b32_e32 v95, v2
	v_mov_b32_e32 v96, v2
	v_mov_b32_e32 v97, v2
	v_mov_b32_e32 v106, v2
	v_mov_b32_e32 v107, v2
	v_mov_b32_e32 v108, v2
	v_mov_b32_e32 v109, v2
	v_mov_b32_e32 v110, v2
	v_mov_b32_e32 v111, v2
	v_mov_b32_e32 v112, v2
	v_mov_b32_e32 v113, v2
	v_mov_b32_e32 v122, v2
	v_mov_b32_e32 v123, v2
	v_mov_b32_e32 v124, v2
	v_mov_b32_e32 v125, v2
	v_mov_b32_e32 v126, v2
	v_mov_b32_e32 v127, v2
	v_mov_b32_e32 v128, v2
	v_mov_b32_e32 v129, v2
	.p2alignl 6, 3212836864

.LBB0_462:
	s_ashr_i32 s27, s26, 31
	s_lshl_b64 s[28:29], s[26:27], 19
	s_add_u32 s28, s8, s28
	s_addc_u32 s29, s9, s29
	s_and_b64 s[30:31], s[6:7], exec
	s_cselect_b32 s13, s29, s35
	s_cselect_b32 s27, s28, s34
	s_ashr_i32 s25, s24, 31
	s_lshl_b64 s[30:31], s[24:25], 19
	s_add_u32 s30, s3, s30
	s_addc_u32 s31, s40, s31
	s_and_b64 s[38:39], s[6:7], exec
	s_cselect_b32 s25, s31, s37
	s_cselect_b32 s57, s30, s36
	s_add_u32 s34, s34, 0x40080
	s_addc_u32 s35, s35, 0
	s_add_u32 s64, s36, 0x100
	v_mov_b32_e32 v2, 0
	s_addc_u32 s65, s37, 0
	s_mov_b32 s66, -2
	s_waitcnt lgkmcnt(0)
	v_mov_b32_e32 v3, v2
	v_mov_b32_e32 v4, v2
	v_mov_b32_e32 v5, v2
	v_mov_b32_e32 v6, v2
	v_mov_b32_e32 v7, v2
	v_mov_b32_e32 v8, v2
	v_mov_b32_e32 v9, v2
	v_mov_b32_e32 v18, v2
	v_mov_b32_e32 v19, v2
	v_mov_b32_e32 v20, v2
	v_mov_b32_e32 v21, v2
	v_mov_b32_e32 v22, v2
	v_mov_b32_e32 v23, v2
	v_mov_b32_e32 v24, v2
	v_mov_b32_e32 v25, v2
	v_mov_b32_e32 v34, v2
	v_mov_b32_e32 v35, v2
	v_mov_b32_e32 v36, v2
	v_mov_b32_e32 v37, v2
	v_mov_b32_e32 v38, v2
	v_mov_b32_e32 v39, v2
	v_mov_b32_e32 v40, v2
	v_mov_b32_e32 v41, v2
	v_mov_b32_e32 v82, v2
	v_mov_b32_e32 v83, v2
	v_mov_b32_e32 v84, v2
	v_mov_b32_e32 v85, v2
	v_mov_b32_e32 v86, v2
	v_mov_b32_e32 v87, v2
	v_mov_b32_e32 v88, v2
	v_mov_b32_e32 v89, v2
	v_mov_b32_e32 v10, v2
	v_mov_b32_e32 v11, v2
	v_mov_b32_e32 v12, v2
	v_mov_b32_e32 v13, v2
	v_mov_b32_e32 v14, v2
	v_mov_b32_e32 v15, v2
	v_mov_b32_e32 v16, v2
	v_mov_b32_e32 v17, v2
	v_mov_b32_e32 v26, v2
	v_mov_b32_e32 v27, v2
	v_mov_b32_e32 v28, v2
	v_mov_b32_e32 v29, v2
	v_mov_b32_e32 v30, v2
	v_mov_b32_e32 v31, v2
	v_mov_b32_e32 v32, v2
	v_mov_b32_e32 v33, v2
	v_mov_b32_e32 v42, v2
	v_mov_b32_e32 v43, v2
	v_mov_b32_e32 v44, v2
	v_mov_b32_e32 v45, v2
	v_mov_b32_e32 v46, v2
	v_mov_b32_e32 v47, v2
	v_mov_b32_e32 v48, v2
	v_mov_b32_e32 v49, v2
	v_mov_b32_e32 v90, v2
	v_mov_b32_e32 v91, v2
	v_mov_b32_e32 v92, v2
	v_mov_b32_e32 v93, v2
	v_mov_b32_e32 v94, v2
	v_mov_b32_e32 v95, v2
	v_mov_b32_e32 v96, v2
	v_mov_b32_e32 v97, v2
	v_mov_b32_e32 v98, v2
	v_mov_b32_e32 v99, v2
	v_mov_b32_e32 v100, v2
	v_mov_b32_e32 v101, v2
	v_mov_b32_e32 v102, v2
	v_mov_b32_e32 v103, v2
	v_mov_b32_e32 v104, v2
	v_mov_b32_e32 v105, v2
	v_mov_b32_e32 v114, v2
	v_mov_b32_e32 v115, v2
	v_mov_b32_e32 v116, v2
	v_mov_b32_e32 v117, v2
	v_mov_b32_e32 v118, v2
	v_mov_b32_e32 v119, v2
	v_mov_b32_e32 v120, v2
	v_mov_b32_e32 v121, v2
	v_mov_b32_e32 v130, v2
	v_mov_b32_e32 v131, v2
	v_mov_b32_e32 v132, v2
	v_mov_b32_e32 v133, v2
	v_mov_b32_e32 v134, v2
	v_mov_b32_e32 v135, v2
	v_mov_b32_e32 v136, v2
	v_mov_b32_e32 v137, v2
	v_mov_b32_e32 v146, v2
	v_mov_b32_e32 v147, v2
	v_mov_b32_e32 v148, v2
	v_mov_b32_e32 v149, v2
	v_mov_b32_e32 v150, v2
	v_mov_b32_e32 v151, v2
	v_mov_b32_e32 v152, v2
	v_mov_b32_e32 v153, v2
	v_mov_b32_e32 v106, v2
	v_mov_b32_e32 v107, v2
	v_mov_b32_e32 v108, v2
	v_mov_b32_e32 v109, v2
	v_mov_b32_e32 v110, v2
	v_mov_b32_e32 v111, v2
	v_mov_b32_e32 v112, v2
	v_mov_b32_e32 v113, v2
	v_mov_b32_e32 v122, v2
	v_mov_b32_e32 v123, v2
	v_mov_b32_e32 v124, v2
	v_mov_b32_e32 v125, v2
	v_mov_b32_e32 v126, v2
	v_mov_b32_e32 v127, v2
	v_mov_b32_e32 v128, v2
	v_mov_b32_e32 v129, v2
	v_mov_b32_e32 v138, v2
	v_mov_b32_e32 v139, v2
	v_mov_b32_e32 v140, v2
	v_mov_b32_e32 v141, v2
	v_mov_b32_e32 v142, v2
	v_mov_b32_e32 v143, v2
	v_mov_b32_e32 v144, v2
	v_mov_b32_e32 v145, v2
	v_mov_b32_e32 v154, v2
	v_mov_b32_e32 v155, v2
	v_mov_b32_e32 v156, v2
	v_mov_b32_e32 v157, v2
	v_mov_b32_e32 v158, v2
	v_mov_b32_e32 v159, v2
	v_mov_b32_e32 v160, v2
	v_mov_b32_e32 v161, v2
	.p2alignl 6, 3212836864

.LBB0_566:
	s_ashr_i32 s21, s20, 31
	s_lshl_b64 s[22:23], s[20:21], 20
	s_add_u32 s22, s40, s22
	s_addc_u32 s23, s41, s23
	s_and_b64 s[24:25], s[4:5], exec
	s_cselect_b32 s21, s23, s27
	s_cselect_b32 s57, s22, s26
	s_ashr_i32 s19, s18, 31
	s_lshl_b64 s[24:25], s[18:19], 20
	s_add_u32 s24, s37, s24
	s_addc_u32 s25, s38, s25
	v_lshl_add_u32 v158, s30, 8, v1
	s_and_b64 s[34:35], s[4:5], exec
	v_add_u32_e32 v156, 0x80, v158
	v_add_u32_e32 v154, 0x90, v158
	v_add_u32_e32 v152, 0xa0, v158
	v_add_u32_e32 v150, 0xb0, v158
	v_mov_b32_e32 v4, v2
	v_mov_b32_e32 v5, v2
	s_cselect_b32 s19, s25, s29
	s_cselect_b32 s64, s24, s28
	v_ashrrev_i32_e32 v159, 31, v158
	v_ashrrev_i32_e32 v157, 31, v156
	v_ashrrev_i32_e32 v155, 31, v154
	v_ashrrev_i32_e32 v153, 31, v152
	v_ashrrev_i32_e32 v151, 31, v150
	s_add_u32 s65, s28, 0x100
	v_mov_b32_e32 v3, v2
	v_mov_b64_e32 v[8:9], v[4:5]
	v_mov_b64_e32 v[12:13], v[4:5]
	v_mov_b64_e32 v[24:25], v[4:5]
	v_mov_b64_e32 v[28:29], v[4:5]
	v_mov_b64_e32 v[40:41], v[4:5]
	v_mov_b64_e32 v[44:45], v[4:5]
	v_mov_b64_e32 v[56:57], v[4:5]
	v_mov_b64_e32 v[60:61], v[4:5]
	v_mov_b64_e32 v[16:17], v[4:5]
	v_mov_b64_e32 v[20:21], v[4:5]
	v_mov_b64_e32 v[32:33], v[4:5]
	v_mov_b64_e32 v[36:37], v[4:5]
	v_mov_b64_e32 v[48:49], v[4:5]
	v_mov_b64_e32 v[52:53], v[4:5]
	v_mov_b64_e32 v[64:65], v[4:5]
	v_mov_b64_e32 v[68:69], v[4:5]
	v_mov_b64_e32 v[72:73], v[4:5]
	v_mov_b64_e32 v[76:77], v[4:5]
	v_mov_b64_e32 v[88:89], v[4:5]
	v_mov_b64_e32 v[92:93], v[4:5]
	v_mov_b64_e32 v[104:105], v[4:5]
	v_mov_b64_e32 v[108:109], v[4:5]
	v_mov_b64_e32 v[120:121], v[4:5]
	v_mov_b64_e32 v[124:125], v[4:5]
	v_mov_b64_e32 v[80:81], v[4:5]
	v_mov_b64_e32 v[84:85], v[4:5]
	v_mov_b64_e32 v[96:97], v[4:5]
	v_mov_b64_e32 v[100:101], v[4:5]
	v_mov_b64_e32 v[112:113], v[4:5]
	v_mov_b64_e32 v[116:117], v[4:5]
	v_mov_b64_e32 v[128:129], v[4:5]
	v_mov_b64_e32 v[132:133], v[4:5]
	v_lshl_add_u64 v[160:161], v[158:159], 2, s[8:9]
	v_lshl_add_u64 v[162:163], v[156:157], 2, s[8:9]
	v_lshl_add_u64 v[164:165], v[154:155], 2, s[8:9]
	v_lshl_add_u64 v[166:167], v[152:153], 2, s[8:9]
	v_lshl_add_u64 v[168:169], v[150:151], 2, s[8:9]
	v_lshl_add_u64 v[170:171], s[26:27], 0, v[142:143]
	v_lshl_add_u64 v[172:173], s[26:27], 0, v[144:145]
	s_addc_u32 s66, s29, 0
	s_mov_b32 s67, -2
	s_mov_b64 s[28:29], 0
	v_mov_b64_e32 v[6:7], v[2:3]
	v_mov_b64_e32 v[10:11], v[2:3]
	v_mov_b64_e32 v[22:23], v[2:3]
	v_mov_b64_e32 v[26:27], v[2:3]
	v_mov_b64_e32 v[38:39], v[2:3]
	v_mov_b64_e32 v[42:43], v[2:3]
	v_mov_b64_e32 v[54:55], v[2:3]
	v_mov_b64_e32 v[58:59], v[2:3]
	v_mov_b64_e32 v[14:15], v[2:3]
	v_mov_b64_e32 v[18:19], v[2:3]
	v_mov_b64_e32 v[30:31], v[2:3]
	v_mov_b64_e32 v[34:35], v[2:3]
	v_mov_b64_e32 v[46:47], v[2:3]
	v_mov_b64_e32 v[50:51], v[2:3]
	v_mov_b64_e32 v[62:63], v[2:3]
	v_mov_b64_e32 v[66:67], v[2:3]
	v_mov_b64_e32 v[70:71], v[2:3]
	v_mov_b64_e32 v[74:75], v[2:3]
	v_mov_b64_e32 v[86:87], v[2:3]
	v_mov_b64_e32 v[90:91], v[2:3]
	v_mov_b64_e32 v[102:103], v[2:3]
	v_mov_b64_e32 v[106:107], v[2:3]
	v_mov_b64_e32 v[118:119], v[2:3]
	v_mov_b64_e32 v[122:123], v[2:3]
	v_mov_b64_e32 v[78:79], v[2:3]
	v_mov_b64_e32 v[82:83], v[2:3]
	v_mov_b64_e32 v[94:95], v[2:3]
	v_mov_b64_e32 v[98:99], v[2:3]
	v_mov_b64_e32 v[110:111], v[2:3]
	v_mov_b64_e32 v[114:115], v[2:3]
	v_mov_b64_e32 v[126:127], v[2:3]
	v_mov_b64_e32 v[130:131], v[2:3]
	s_branch .LBB0_568
	.p2alignl 6, 3212836864

.LBB0_706:
	s_ashr_i32 s23, s22, 31
	s_lshl_b64 s[24:25], s[22:23], 20
	s_add_u32 s24, s44, s24
	s_addc_u32 s25, s45, s25
	s_and_b64 s[26:27], s[4:5], exec
	s_cselect_b32 s23, s25, s31
	s_cselect_b32 s69, s24, s30
	s_ashr_i32 s21, s20, 31
	s_lshl_b64 s[26:27], s[20:21], 20
	s_add_u32 s26, s56, s26
	s_addc_u32 s27, s57, s27
	s_and_b64 s[36:37], s[4:5], exec
	s_cselect_b32 s21, s27, s35
	s_cselect_b32 s38, s26, s34
	s_add_u32 s30, s30, 0x80080
	s_addc_u32 s31, s31, 0
	s_add_u32 s39, s34, 0x100
	v_mov_b32_e32 v2, 0
	s_addc_u32 s70, s35, 0
	s_mov_b32 s71, -2
	v_mov_b32_e32 v3, v2
	v_mov_b32_e32 v4, v2
	v_mov_b32_e32 v5, v2
	v_mov_b32_e32 v6, v2
	v_mov_b32_e32 v7, v2
	v_mov_b32_e32 v8, v2
	v_mov_b32_e32 v9, v2
	v_mov_b32_e32 v18, v2
	v_mov_b32_e32 v19, v2
	v_mov_b32_e32 v20, v2
	v_mov_b32_e32 v21, v2
	v_mov_b32_e32 v22, v2
	v_mov_b32_e32 v23, v2
	v_mov_b32_e32 v24, v2
	v_mov_b32_e32 v25, v2
	v_mov_b32_e32 v34, v2
	v_mov_b32_e32 v35, v2
	v_mov_b32_e32 v36, v2
	v_mov_b32_e32 v37, v2
	v_mov_b32_e32 v38, v2
	v_mov_b32_e32 v39, v2
	v_mov_b32_e32 v40, v2
	v_mov_b32_e32 v41, v2
	v_mov_b32_e32 v50, v2
	v_mov_b32_e32 v51, v2
	v_mov_b32_e32 v52, v2
	v_mov_b32_e32 v53, v2
	v_mov_b32_e32 v54, v2
	v_mov_b32_e32 v55, v2
	v_mov_b32_e32 v56, v2
	v_mov_b32_e32 v57, v2
	v_mov_b32_e32 v10, v2
	v_mov_b32_e32 v11, v2
	v_mov_b32_e32 v12, v2
	v_mov_b32_e32 v13, v2
	v_mov_b32_e32 v14, v2
	v_mov_b32_e32 v15, v2
	v_mov_b32_e32 v16, v2
	v_mov_b32_e32 v17, v2
	v_mov_b32_e32 v26, v2
	v_mov_b32_e32 v27, v2
	v_mov_b32_e32 v28, v2
	v_mov_b32_e32 v29, v2
	v_mov_b32_e32 v30, v2
	v_mov_b32_e32 v31, v2
	v_mov_b32_e32 v32, v2
	v_mov_b32_e32 v33, v2
	v_mov_b32_e32 v42, v2
	v_mov_b32_e32 v43, v2
	v_mov_b32_e32 v44, v2
	v_mov_b32_e32 v45, v2
	v_mov_b32_e32 v46, v2
	v_mov_b32_e32 v47, v2
	v_mov_b32_e32 v48, v2
	v_mov_b32_e32 v49, v2
	v_mov_b32_e32 v58, v2
	v_mov_b32_e32 v59, v2
	v_mov_b32_e32 v60, v2
	v_mov_b32_e32 v61, v2
	v_mov_b32_e32 v62, v2
	v_mov_b32_e32 v63, v2
	v_mov_b32_e32 v64, v2
	v_mov_b32_e32 v65, v2
	v_mov_b32_e32 v66, v2
	v_mov_b32_e32 v67, v2
	v_mov_b32_e32 v68, v2
	v_mov_b32_e32 v69, v2
	v_mov_b32_e32 v70, v2
	v_mov_b32_e32 v71, v2
	v_mov_b32_e32 v72, v2
	v_mov_b32_e32 v73, v2
	v_mov_b32_e32 v82, v2
	v_mov_b32_e32 v83, v2
	v_mov_b32_e32 v84, v2
	v_mov_b32_e32 v85, v2
	v_mov_b32_e32 v86, v2
	v_mov_b32_e32 v87, v2
	v_mov_b32_e32 v88, v2
	v_mov_b32_e32 v89, v2
	v_mov_b32_e32 v98, v2
	v_mov_b32_e32 v99, v2
	v_mov_b32_e32 v100, v2
	v_mov_b32_e32 v101, v2
	v_mov_b32_e32 v102, v2
	v_mov_b32_e32 v103, v2
	v_mov_b32_e32 v104, v2
	v_mov_b32_e32 v105, v2
	v_mov_b32_e32 v114, v2
	v_mov_b32_e32 v115, v2
	v_mov_b32_e32 v116, v2
	v_mov_b32_e32 v117, v2
	v_mov_b32_e32 v118, v2
	v_mov_b32_e32 v119, v2
	v_mov_b32_e32 v120, v2
	v_mov_b32_e32 v121, v2
	v_mov_b32_e32 v74, v2
	v_mov_b32_e32 v75, v2
	v_mov_b32_e32 v76, v2
	v_mov_b32_e32 v77, v2
	v_mov_b32_e32 v78, v2
	v_mov_b32_e32 v79, v2
	v_mov_b32_e32 v80, v2
	v_mov_b32_e32 v81, v2
	v_mov_b32_e32 v90, v2
	v_mov_b32_e32 v91, v2
	v_mov_b32_e32 v92, v2
	v_mov_b32_e32 v93, v2
	v_mov_b32_e32 v94, v2
	v_mov_b32_e32 v95, v2
	v_mov_b32_e32 v96, v2
	v_mov_b32_e32 v97, v2
	v_mov_b32_e32 v106, v2
	v_mov_b32_e32 v107, v2
	v_mov_b32_e32 v108, v2
	v_mov_b32_e32 v109, v2
	v_mov_b32_e32 v110, v2
	v_mov_b32_e32 v111, v2
	v_mov_b32_e32 v112, v2
	v_mov_b32_e32 v113, v2
	v_mov_b32_e32 v122, v2
	v_mov_b32_e32 v123, v2
	v_mov_b32_e32 v124, v2
	v_mov_b32_e32 v125, v2
	v_mov_b32_e32 v126, v2
	v_mov_b32_e32 v127, v2
	v_mov_b32_e32 v128, v2
	v_mov_b32_e32 v129, v2
	.p2alignl 6, 3212836864

.LBB0_781:
	s_ashr_i32 s97, s96, 31
	s_lshl_b64 s[22:23], s[96:97], 22
	s_add_u32 s24, s0, s22
	s_addc_u32 s25, s1, s23
	s_and_b64 s[22:23], s[42:43], exec
	s_cselect_b32 s97, s25, s19
	s_cselect_b32 s38, s24, s18
	s_ashr_i32 s45, s44, 31
	s_lshl_b64 s[22:23], s[44:45], 22
	s_add_u32 s22, s26, s22
	s_addc_u32 s23, s27, s23
	s_and_b64 s[64:65], s[42:43], exec
	s_cselect_b32 s39, s23, s21
	s_cselect_b32 s45, s22, s20
	s_add_u32 vcc_lo, s18, 0x200080
	s_addc_u32 vcc_hi, s19, 0
	s_add_u32 s64, s20, 0x100
	v_mov_b32_e32 v2, 0
	s_addc_u32 s65, s21, 0
	s_mov_b32 s66, -2
	v_mov_b32_e32 v3, v2
	v_mov_b32_e32 v4, v2
	v_mov_b32_e32 v5, v2
	v_mov_b32_e32 v6, v2
	v_mov_b32_e32 v7, v2
	v_mov_b32_e32 v8, v2
	v_mov_b32_e32 v9, v2
	v_mov_b32_e32 v10, v2
	v_mov_b32_e32 v11, v2
	v_mov_b32_e32 v12, v2
	v_mov_b32_e32 v13, v2
	v_mov_b32_e32 v14, v2
	v_mov_b32_e32 v15, v2
	v_mov_b32_e32 v16, v2
	v_mov_b32_e32 v17, v2
	v_mov_b32_e32 v26, v2
	v_mov_b32_e32 v27, v2
	v_mov_b32_e32 v28, v2
	v_mov_b32_e32 v29, v2
	v_mov_b32_e32 v30, v2
	v_mov_b32_e32 v31, v2
	v_mov_b32_e32 v32, v2
	v_mov_b32_e32 v33, v2
	v_mov_b32_e32 v42, v2
	v_mov_b32_e32 v43, v2
	v_mov_b32_e32 v44, v2
	v_mov_b32_e32 v45, v2
	v_mov_b32_e32 v46, v2
	v_mov_b32_e32 v47, v2
	v_mov_b32_e32 v48, v2
	v_mov_b32_e32 v49, v2
	v_mov_b32_e32 v18, v2
	v_mov_b32_e32 v19, v2
	v_mov_b32_e32 v20, v2
	v_mov_b32_e32 v21, v2
	v_mov_b32_e32 v22, v2
	v_mov_b32_e32 v23, v2
	v_mov_b32_e32 v24, v2
	v_mov_b32_e32 v25, v2
	v_mov_b32_e32 v34, v2
	v_mov_b32_e32 v35, v2
	v_mov_b32_e32 v36, v2
	v_mov_b32_e32 v37, v2
	v_mov_b32_e32 v38, v2
	v_mov_b32_e32 v39, v2
	v_mov_b32_e32 v40, v2
	v_mov_b32_e32 v41, v2
	v_mov_b32_e32 v50, v2
	v_mov_b32_e32 v51, v2
	v_mov_b32_e32 v52, v2
	v_mov_b32_e32 v53, v2
	v_mov_b32_e32 v54, v2
	v_mov_b32_e32 v55, v2
	v_mov_b32_e32 v56, v2
	v_mov_b32_e32 v57, v2
	v_mov_b32_e32 v58, v2
	v_mov_b32_e32 v59, v2
	v_mov_b32_e32 v60, v2
	v_mov_b32_e32 v61, v2
	v_mov_b32_e32 v62, v2
	v_mov_b32_e32 v63, v2
	v_mov_b32_e32 v64, v2
	v_mov_b32_e32 v65, v2
	v_mov_b32_e32 v66, v2
	v_mov_b32_e32 v67, v2
	v_mov_b32_e32 v68, v2
	v_mov_b32_e32 v69, v2
	v_mov_b32_e32 v70, v2
	v_mov_b32_e32 v71, v2
	v_mov_b32_e32 v72, v2
	v_mov_b32_e32 v73, v2
	v_mov_b32_e32 v74, v2
	v_mov_b32_e32 v75, v2
	v_mov_b32_e32 v76, v2
	v_mov_b32_e32 v77, v2
	v_mov_b32_e32 v78, v2
	v_mov_b32_e32 v79, v2
	v_mov_b32_e32 v80, v2
	v_mov_b32_e32 v81, v2
	v_mov_b32_e32 v90, v2
	v_mov_b32_e32 v91, v2
	v_mov_b32_e32 v92, v2
	v_mov_b32_e32 v93, v2
	v_mov_b32_e32 v94, v2
	v_mov_b32_e32 v95, v2
	v_mov_b32_e32 v96, v2
	v_mov_b32_e32 v97, v2
	v_mov_b32_e32 v106, v2
	v_mov_b32_e32 v107, v2
	v_mov_b32_e32 v108, v2
	v_mov_b32_e32 v109, v2
	v_mov_b32_e32 v110, v2
	v_mov_b32_e32 v111, v2
	v_mov_b32_e32 v112, v2
	v_mov_b32_e32 v113, v2
	v_mov_b32_e32 v82, v2
	v_mov_b32_e32 v83, v2
	v_mov_b32_e32 v84, v2
	v_mov_b32_e32 v85, v2
	v_mov_b32_e32 v86, v2
	v_mov_b32_e32 v87, v2
	v_mov_b32_e32 v88, v2
	v_mov_b32_e32 v89, v2
	v_mov_b32_e32 v98, v2
	v_mov_b32_e32 v99, v2
	v_mov_b32_e32 v100, v2
	v_mov_b32_e32 v101, v2
	v_mov_b32_e32 v102, v2
	v_mov_b32_e32 v103, v2
	v_mov_b32_e32 v104, v2
	v_mov_b32_e32 v105, v2
	v_mov_b32_e32 v114, v2
	v_mov_b32_e32 v115, v2
	v_mov_b32_e32 v116, v2
	v_mov_b32_e32 v117, v2
	v_mov_b32_e32 v118, v2
	v_mov_b32_e32 v119, v2
	v_mov_b32_e32 v120, v2
	v_mov_b32_e32 v121, v2
	v_mov_b32_e32 v122, v2
	v_mov_b32_e32 v123, v2
	v_mov_b32_e32 v124, v2
	v_mov_b32_e32 v125, v2
	v_mov_b32_e32 v126, v2
	v_mov_b32_e32 v127, v2
	v_mov_b32_e32 v128, v2
	v_mov_b32_e32 v129, v2
	.p2alignl 6, 3212836864

.LBB0_856:
	s_ashr_i32 s97, s96, 31
	v_cmp_lt_i64_e64 s[38:39], s[12:13], v[150:151]
	s_lshl_b64 s[12:13], s[96:97], 20
	s_add_u32 s12, s24, s12
	s_addc_u32 s13, s25, s13
	s_and_b64 s[14:15], s[38:39], exec
	s_cselect_b32 s97, s13, s19
	s_cselect_b32 vcc_lo, s12, s18
	s_ashr_i32 s45, s44, 31
	s_lshl_b64 s[14:15], s[44:45], 20
	s_add_u32 s14, s56, s14
	s_addc_u32 s15, s57, s15
	s_and_b64 s[22:23], s[38:39], exec
	s_cselect_b32 s45, s15, s21
	s_cselect_b32 vcc_hi, s14, s20
	s_add_u32 s18, s18, 0x80080
	s_addc_u32 s19, s19, 0
	s_add_u32 s64, s20, 0x100
	v_mov_b32_e32 v2, 0
	s_addc_u32 s65, s21, 0
	s_mov_b32 s66, -2
	v_mov_b32_e32 v3, v2
	v_mov_b32_e32 v4, v2
	v_mov_b32_e32 v5, v2
	v_mov_b32_e32 v6, v2
	v_mov_b32_e32 v7, v2
	v_mov_b32_e32 v8, v2
	v_mov_b32_e32 v9, v2
	v_mov_b32_e32 v18, v2
	v_mov_b32_e32 v19, v2
	v_mov_b32_e32 v20, v2
	v_mov_b32_e32 v21, v2
	v_mov_b32_e32 v22, v2
	v_mov_b32_e32 v23, v2
	v_mov_b32_e32 v24, v2
	v_mov_b32_e32 v25, v2
	v_mov_b32_e32 v34, v2
	v_mov_b32_e32 v35, v2
	v_mov_b32_e32 v36, v2
	v_mov_b32_e32 v37, v2
	v_mov_b32_e32 v38, v2
	v_mov_b32_e32 v39, v2
	v_mov_b32_e32 v40, v2
	v_mov_b32_e32 v41, v2
	v_mov_b32_e32 v50, v2
	v_mov_b32_e32 v51, v2
	v_mov_b32_e32 v52, v2
	v_mov_b32_e32 v53, v2
	v_mov_b32_e32 v54, v2
	v_mov_b32_e32 v55, v2
	v_mov_b32_e32 v56, v2
	v_mov_b32_e32 v57, v2
	v_mov_b32_e32 v10, v2
	v_mov_b32_e32 v11, v2
	v_mov_b32_e32 v12, v2
	v_mov_b32_e32 v13, v2
	v_mov_b32_e32 v14, v2
	v_mov_b32_e32 v15, v2
	v_mov_b32_e32 v16, v2
	v_mov_b32_e32 v17, v2
	v_mov_b32_e32 v26, v2
	v_mov_b32_e32 v27, v2
	v_mov_b32_e32 v28, v2
	v_mov_b32_e32 v29, v2
	v_mov_b32_e32 v30, v2
	v_mov_b32_e32 v31, v2
	v_mov_b32_e32 v32, v2
	v_mov_b32_e32 v33, v2
	v_mov_b32_e32 v42, v2
	v_mov_b32_e32 v43, v2
	v_mov_b32_e32 v44, v2
	v_mov_b32_e32 v45, v2
	v_mov_b32_e32 v46, v2
	v_mov_b32_e32 v47, v2
	v_mov_b32_e32 v48, v2
	v_mov_b32_e32 v49, v2
	v_mov_b32_e32 v58, v2
	v_mov_b32_e32 v59, v2
	v_mov_b32_e32 v60, v2
	v_mov_b32_e32 v61, v2
	v_mov_b32_e32 v62, v2
	v_mov_b32_e32 v63, v2
	v_mov_b32_e32 v64, v2
	v_mov_b32_e32 v65, v2
	v_mov_b32_e32 v66, v2
	v_mov_b32_e32 v67, v2
	v_mov_b32_e32 v68, v2
	v_mov_b32_e32 v69, v2
	v_mov_b32_e32 v70, v2
	v_mov_b32_e32 v71, v2
	v_mov_b32_e32 v72, v2
	v_mov_b32_e32 v73, v2
	v_mov_b32_e32 v82, v2
	v_mov_b32_e32 v83, v2
	v_mov_b32_e32 v84, v2
	v_mov_b32_e32 v85, v2
	v_mov_b32_e32 v86, v2
	v_mov_b32_e32 v87, v2
	v_mov_b32_e32 v88, v2
	v_mov_b32_e32 v89, v2
	v_mov_b32_e32 v98, v2
	v_mov_b32_e32 v99, v2
	v_mov_b32_e32 v100, v2
	v_mov_b32_e32 v101, v2
	v_mov_b32_e32 v102, v2
	v_mov_b32_e32 v103, v2
	v_mov_b32_e32 v104, v2
	v_mov_b32_e32 v105, v2
	v_mov_b32_e32 v114, v2
	v_mov_b32_e32 v115, v2
	v_mov_b32_e32 v116, v2
	v_mov_b32_e32 v117, v2
	v_mov_b32_e32 v118, v2
	v_mov_b32_e32 v119, v2
	v_mov_b32_e32 v120, v2
	v_mov_b32_e32 v121, v2
	v_mov_b32_e32 v74, v2
	v_mov_b32_e32 v75, v2
	v_mov_b32_e32 v76, v2
	v_mov_b32_e32 v77, v2
	v_mov_b32_e32 v78, v2
	v_mov_b32_e32 v79, v2
	v_mov_b32_e32 v80, v2
	v_mov_b32_e32 v81, v2
	v_mov_b32_e32 v90, v2
	v_mov_b32_e32 v91, v2
	v_mov_b32_e32 v92, v2
	v_mov_b32_e32 v93, v2
	v_mov_b32_e32 v94, v2
	v_mov_b32_e32 v95, v2
	v_mov_b32_e32 v96, v2
	v_mov_b32_e32 v97, v2
	v_mov_b32_e32 v106, v2
	v_mov_b32_e32 v107, v2
	v_mov_b32_e32 v108, v2
	v_mov_b32_e32 v109, v2
	v_mov_b32_e32 v110, v2
	v_mov_b32_e32 v111, v2
	v_mov_b32_e32 v112, v2
	v_mov_b32_e32 v113, v2
	v_mov_b32_e32 v122, v2
	v_mov_b32_e32 v123, v2
	v_mov_b32_e32 v124, v2
	v_mov_b32_e32 v125, v2
	v_mov_b32_e32 v126, v2
	v_mov_b32_e32 v127, v2
	v_mov_b32_e32 v128, v2
	v_mov_b32_e32 v129, v2
	.p2alignl 6, 3212836864

.LBB0_931:
	s_ashr_i32 s43, s42, 31
	v_cmp_lt_i64_e64 s[38:39], s[18:19], v[134:135]
	s_lshl_b64 s[18:19], s[42:43], 22
	s_add_u32 s18, s0, s18
	s_addc_u32 s19, s1, s19
	s_and_b64 s[20:21], s[38:39], exec
	s_cselect_b32 s43, s19, s25
	s_cselect_b32 s96, s18, s24
	s_ashr_i32 s41, s40, 31
	s_lshl_b64 s[20:21], s[40:41], 22
	s_add_u32 s20, s26, s20
	s_addc_u32 s21, s27, s21
	s_and_b64 s[44:45], s[38:39], exec
	s_cselect_b32 s41, s21, s23
	s_cselect_b32 s97, s20, s22
	s_add_u32 s44, s24, 0x200080
	s_addc_u32 s45, s25, 0
	s_add_u32 s64, s22, 0x100
	v_mov_b32_e32 v2, 0
	s_addc_u32 s65, s23, 0
	s_mov_b32 s66, -2
	v_mov_b32_e32 v3, v2
	v_mov_b32_e32 v4, v2
	v_mov_b32_e32 v5, v2
	v_mov_b32_e32 v6, v2
	v_mov_b32_e32 v7, v2
	v_mov_b32_e32 v8, v2
	v_mov_b32_e32 v9, v2
	v_mov_b32_e32 v10, v2
	v_mov_b32_e32 v11, v2
	v_mov_b32_e32 v12, v2
	v_mov_b32_e32 v13, v2
	v_mov_b32_e32 v14, v2
	v_mov_b32_e32 v15, v2
	v_mov_b32_e32 v16, v2
	v_mov_b32_e32 v17, v2
	v_mov_b32_e32 v26, v2
	v_mov_b32_e32 v27, v2
	v_mov_b32_e32 v28, v2
	v_mov_b32_e32 v29, v2
	v_mov_b32_e32 v30, v2
	v_mov_b32_e32 v31, v2
	v_mov_b32_e32 v32, v2
	v_mov_b32_e32 v33, v2
	v_mov_b32_e32 v42, v2
	v_mov_b32_e32 v43, v2
	v_mov_b32_e32 v44, v2
	v_mov_b32_e32 v45, v2
	v_mov_b32_e32 v46, v2
	v_mov_b32_e32 v47, v2
	v_mov_b32_e32 v48, v2
	v_mov_b32_e32 v49, v2
	v_mov_b32_e32 v18, v2
	v_mov_b32_e32 v19, v2
	v_mov_b32_e32 v20, v2
	v_mov_b32_e32 v21, v2
	v_mov_b32_e32 v22, v2
	v_mov_b32_e32 v23, v2
	v_mov_b32_e32 v24, v2
	v_mov_b32_e32 v25, v2
	v_mov_b32_e32 v34, v2
	v_mov_b32_e32 v35, v2
	v_mov_b32_e32 v36, v2
	v_mov_b32_e32 v37, v2
	v_mov_b32_e32 v38, v2
	v_mov_b32_e32 v39, v2
	v_mov_b32_e32 v40, v2
	v_mov_b32_e32 v41, v2
	v_mov_b32_e32 v50, v2
	v_mov_b32_e32 v51, v2
	v_mov_b32_e32 v52, v2
	v_mov_b32_e32 v53, v2
	v_mov_b32_e32 v54, v2
	v_mov_b32_e32 v55, v2
	v_mov_b32_e32 v56, v2
	v_mov_b32_e32 v57, v2
	v_mov_b32_e32 v58, v2
	v_mov_b32_e32 v59, v2
	v_mov_b32_e32 v60, v2
	v_mov_b32_e32 v61, v2
	v_mov_b32_e32 v62, v2
	v_mov_b32_e32 v63, v2
	v_mov_b32_e32 v64, v2
	v_mov_b32_e32 v65, v2
	v_mov_b32_e32 v66, v2
	v_mov_b32_e32 v67, v2
	v_mov_b32_e32 v68, v2
	v_mov_b32_e32 v69, v2
	v_mov_b32_e32 v70, v2
	v_mov_b32_e32 v71, v2
	v_mov_b32_e32 v72, v2
	v_mov_b32_e32 v73, v2
	v_mov_b32_e32 v74, v2
	v_mov_b32_e32 v75, v2
	v_mov_b32_e32 v76, v2
	v_mov_b32_e32 v77, v2
	v_mov_b32_e32 v78, v2
	v_mov_b32_e32 v79, v2
	v_mov_b32_e32 v80, v2
	v_mov_b32_e32 v81, v2
	v_mov_b32_e32 v90, v2
	v_mov_b32_e32 v91, v2
	v_mov_b32_e32 v92, v2
	v_mov_b32_e32 v93, v2
	v_mov_b32_e32 v94, v2
	v_mov_b32_e32 v95, v2
	v_mov_b32_e32 v96, v2
	v_mov_b32_e32 v97, v2
	v_mov_b32_e32 v106, v2
	v_mov_b32_e32 v107, v2
	v_mov_b32_e32 v108, v2
	v_mov_b32_e32 v109, v2
	v_mov_b32_e32 v110, v2
	v_mov_b32_e32 v111, v2
	v_mov_b32_e32 v112, v2
	v_mov_b32_e32 v113, v2
	v_mov_b32_e32 v82, v2
	v_mov_b32_e32 v83, v2
	v_mov_b32_e32 v84, v2
	v_mov_b32_e32 v85, v2
	v_mov_b32_e32 v86, v2
	v_mov_b32_e32 v87, v2
	v_mov_b32_e32 v88, v2
	v_mov_b32_e32 v89, v2
	v_mov_b32_e32 v98, v2
	v_mov_b32_e32 v99, v2
	v_mov_b32_e32 v100, v2
	v_mov_b32_e32 v101, v2
	v_mov_b32_e32 v102, v2
	v_mov_b32_e32 v103, v2
	v_mov_b32_e32 v104, v2
	v_mov_b32_e32 v105, v2
	v_mov_b32_e32 v114, v2
	v_mov_b32_e32 v115, v2
	v_mov_b32_e32 v116, v2
	v_mov_b32_e32 v117, v2
	v_mov_b32_e32 v118, v2
	v_mov_b32_e32 v119, v2
	v_mov_b32_e32 v120, v2
	v_mov_b32_e32 v121, v2
	v_mov_b32_e32 v122, v2
	v_mov_b32_e32 v123, v2
	v_mov_b32_e32 v124, v2
	v_mov_b32_e32 v125, v2
	v_mov_b32_e32 v126, v2
	v_mov_b32_e32 v127, v2
	v_mov_b32_e32 v128, v2
	v_mov_b32_e32 v129, v2
	.p2alignl 6, 3212836864
